# v69 stack with each GEMM load segment's vmcnt and lgkmcnt waits merged into one s_waitcnt and the redundant loop-top lgkmcnt wait dropped
# baseline (speedup 1.0000x reference)
; #define PG8_STAGE(bufoff, gbase, voff) do { _Pragma("unroll") for (int _i = 0; _i < 2; ++_i) \
;         __builtin_amdgcn_global_load_lds((const unsigned*)((const char*)(gbase) + (voff)[_i]), (LAS unsigned*)(lds + (bufoff) + ldsw + _i * 8192), 16, 0, 0); } while (0)
; #define PG8_LDA(dst, b, h) do { _Pragma("unroll") for (int m = 0; m < 4; ++m) _Pragma("unroll") for (int k = 0; k < 2; ++k) dst[m][k] = *(const LAS bf16x8*)(lds + PG8_SA(b, h) + aoff + m * 2048 + k * 1024); } while (0)
; #define PG8_LDB(dst, b, h) do { _Pragma("unroll") for (int n = 0; n < 2; ++n) _Pragma("unroll") for (int k = 0; k < 2; ++k) dst[n][k] = *(const LAS bf16x8*)(lds + PG8_SB(b, h) + boff + n * 2048 + k * 1024); } while (0)
; #define PG8_MMA(ai, bj, At, Bt) do { __builtin_amdgcn_s_setprio(1); _Pragma("unroll") for (int m = 0; m < 4; ++m) _Pragma("unroll") for (int n = 0; n < 2; ++n) _Pragma("unroll") for (int k = 0; k < 2; ++k) \
;         acc[ai][bj][m][n] = __builtin_amdgcn_mfma_f32_16x16x32_bf16(Bt[n][k], At[m][k], acc[ai][bj][m][n], 0, 0, 0); __builtin_amdgcn_s_setprio(0); } while (0)
; #define PG8_WAIT_V(n) asm volatile("s_waitcnt vmcnt(" #n ")" ::: "memory")
; #define PG8_WAIT_L(n) asm volatile("s_waitcnt lgkmcnt(" #n ")" ::: "memory")
; #define PG8_BAR __builtin_amdgcn_s_barrier()
; #define PG8_SCHED __builtin_amdgcn_sched_barrier(0)
; __device__ __forceinline__ void gemm_phase(LAS unsigned char* lds, const Gemm g, const StaticOrder& S, const Epi& E) {
;     ...
;             PG8_LDB(B0, 0, 0); PG8_LDB(B1, 0, 1); PG8_SCHED; PG8_LDA(At, 0, 0); PG8_STAGE(PG8_SA(1, 1), a1 + hstepA, voffA);
;             PG8_WAIT_V(8); PG8_WAIT_L(0); PG8_BAR; PG8_MMA(0, 0, At, B0); PG8_MMA(0, 1, At, B1); PG8_BAR; PG8_SCHED;
;             PG8_LDA(At, 0, 1); PG8_STAGE(PG8_SB(0, 0), b2, voffB); PG8_STAGE(PG8_SB(0, 1), b2 + hstepB, voffB); PG8_STAGE(PG8_SA(0, 0), a2, voffA);
;             PG8_WAIT_V(8); PG8_WAIT_L(0); PG8_BAR; PG8_MMA(1, 0, At, B0); PG8_MMA(1, 1, At, B1); PG8_BAR; PG8_SCHED;
.LBB0_177:
	ds_read_b128 v[130:133], v226
	ds_read_b128 v[134:137], v226 offset:1024
	ds_read_b128 v[138:141], v226 offset:2048
	ds_read_b128 v[142:145], v226 offset:3072
	ds_read_b128 v[146:149], v227
	ds_read_b128 v[150:153], v227 offset:1024
	ds_read_b128 v[154:157], v227 offset:2048
	ds_read_b128 v[182:185], v227 offset:3072
	s_add_i32 s27, s17, 2
	s_add_u32 s2, s0, 0x80
	s_addc_u32 s3, s1, 0
	s_cmp_eq_u32 s85, s17
	s_cselect_b32 s3, s7, s3
	s_cselect_b32 s2, s6, s2
	s_cselect_b32 s41, s95, s16
	s_cselect_b32 s40, s94, s5
	s_add_i32 m0, s71, 0xc000
	ds_read_b128 v[186:189], v217
	ds_read_b128 v[190:193], v217 offset:1024
	ds_read_b128 v[194:197], v217 offset:2048
	ds_read_b128 v[198:201], v217 offset:3072
	ds_read_b128 v[202:205], v217 offset:4096
	ds_read_b128 v[206:209], v217 offset:5120
	ds_read_b128 v[218:221], v217 offset:6144
	ds_read_b128 v[222:225], v217 offset:7168
	global_load_lds_dwordx4 v178, s[0:1]
	s_add_i32 m0, s71, 0xe000
	s_nop 0
	global_load_lds_dwordx4 v180, s[0:1]
	s_waitcnt vmcnt(8) lgkmcnt(0)
	s_barrier
	s_setprio 1
	v_mfma_f32_16x16x32_bf16 v[114:117], v[130:133], v[186:189], v[114:117]
	v_mfma_f32_16x16x32_bf16 v[126:129], v[138:141], v[186:189], v[126:129]
	v_mfma_f32_16x16x32_bf16 v[110:113], v[130:133], v[194:197], v[110:113]
	v_mfma_f32_16x16x32_bf16 v[102:105], v[138:141], v[194:197], v[102:105]
	v_mfma_f32_16x16x32_bf16 v[94:97], v[130:133], v[202:205], v[94:97]
	v_mfma_f32_16x16x32_bf16 v[86:89], v[138:141], v[202:205], v[86:89]
	v_mfma_f32_16x16x32_bf16 v[78:81], v[130:133], v[218:221], v[78:81]
	v_mfma_f32_16x16x32_bf16 v[70:73], v[138:141], v[218:221], v[70:73]
	v_mfma_f32_16x16x32_bf16 v[114:117], v[134:137], v[190:193], v[114:117]
	v_mfma_f32_16x16x32_bf16 v[126:129], v[142:145], v[190:193], v[126:129]
	v_mfma_f32_16x16x32_bf16 v[110:113], v[134:137], v[198:201], v[110:113]
	v_mfma_f32_16x16x32_bf16 v[102:105], v[142:145], v[198:201], v[102:105]
	v_mfma_f32_16x16x32_bf16 v[94:97], v[134:137], v[206:209], v[94:97]
	v_mfma_f32_16x16x32_bf16 v[86:89], v[142:145], v[206:209], v[86:89]
	v_mfma_f32_16x16x32_bf16 v[78:81], v[134:137], v[222:225], v[78:81]
	v_mfma_f32_16x16x32_bf16 v[70:73], v[142:145], v[222:225], v[70:73]
	v_mfma_f32_16x16x32_bf16 v[122:125], v[146:149], v[186:189], v[122:125]
	v_mfma_f32_16x16x32_bf16 v[118:121], v[154:157], v[186:189], v[118:121]
	v_mfma_f32_16x16x32_bf16 v[106:109], v[146:149], v[194:197], v[106:109]
	v_mfma_f32_16x16x32_bf16 v[98:101], v[154:157], v[194:197], v[98:101]
	v_mfma_f32_16x16x32_bf16 v[90:93], v[146:149], v[202:205], v[90:93]
	v_mfma_f32_16x16x32_bf16 v[82:85], v[154:157], v[202:205], v[82:85]
	v_mfma_f32_16x16x32_bf16 v[74:77], v[146:149], v[218:221], v[74:77]
	v_mfma_f32_16x16x32_bf16 v[66:69], v[154:157], v[218:221], v[66:69]
	v_mfma_f32_16x16x32_bf16 v[122:125], v[150:153], v[190:193], v[122:125]
	v_mfma_f32_16x16x32_bf16 v[118:121], v[182:185], v[190:193], v[118:121]
	v_mfma_f32_16x16x32_bf16 v[106:109], v[150:153], v[198:201], v[106:109]
	v_mfma_f32_16x16x32_bf16 v[98:101], v[182:185], v[198:201], v[98:101]
	v_mfma_f32_16x16x32_bf16 v[90:93], v[150:153], v[206:209], v[90:93]
	v_mfma_f32_16x16x32_bf16 v[82:85], v[182:185], v[206:209], v[82:85]
	v_mfma_f32_16x16x32_bf16 v[74:77], v[150:153], v[222:225], v[74:77]
	v_mfma_f32_16x16x32_bf16 v[66:69], v[182:185], v[222:225], v[66:69]
	s_setprio 0
	s_barrier
	s_add_i32 s17, s39, s70
	s_mov_b32 m0, s17
	ds_read_b128 v[186:189], v217 offset:16384
	ds_read_b128 v[190:193], v217 offset:17408
	ds_read_b128 v[194:197], v217 offset:18432
	ds_read_b128 v[198:201], v217 offset:19456
	ds_read_b128 v[202:205], v217 offset:20480
	ds_read_b128 v[206:209], v217 offset:21504
	ds_read_b128 v[218:221], v217 offset:22528
	ds_read_b128 v[222:225], v217 offset:23552
	global_load_lds_dwordx4 v160, s[40:41]
	s_add_i32 m0, s17, 0x2000
	s_add_i32 s17, s24, s70
	global_load_lds_dwordx4 v164, s[40:41]
	s_add_u32 s40, s40, s52
	s_addc_u32 s41, s41, s53
	s_mov_b32 m0, s17
	s_nop 0
	global_load_lds_dwordx4 v160, s[40:41]
	s_add_i32 m0, s17, 0x2000
	s_nop 0
	global_load_lds_dwordx4 v164, s[40:41]
	s_mov_b32 m0, s71
	s_nop 0
	global_load_lds_dwordx4 v158, s[2:3]
	s_mov_b32 m0, s34
	s_nop 0
	global_load_lds_dwordx4 v162, s[2:3]
	s_waitcnt vmcnt(8) lgkmcnt(0)
	s_barrier
	s_setprio 1
	v_mfma_f32_16x16x32_bf16 v[62:65], v[130:133], v[186:189], v[62:65]
	v_mfma_f32_16x16x32_bf16 v[54:57], v[138:141], v[186:189], v[54:57]
	v_mfma_f32_16x16x32_bf16 v[46:49], v[130:133], v[194:197], v[46:49]
	v_mfma_f32_16x16x32_bf16 v[38:41], v[138:141], v[194:197], v[38:41]
	v_mfma_f32_16x16x32_bf16 v[30:33], v[130:133], v[202:205], v[30:33]
	v_mfma_f32_16x16x32_bf16 v[22:25], v[138:141], v[202:205], v[22:25]
	v_mfma_f32_16x16x32_bf16 v[14:17], v[130:133], v[218:221], v[14:17]
	v_mfma_f32_16x16x32_bf16 v[6:9], v[138:141], v[218:221], v[6:9]
	v_mfma_f32_16x16x32_bf16 v[62:65], v[134:137], v[190:193], v[62:65]
	v_mfma_f32_16x16x32_bf16 v[54:57], v[142:145], v[190:193], v[54:57]
	v_mfma_f32_16x16x32_bf16 v[46:49], v[134:137], v[198:201], v[46:49]
	v_mfma_f32_16x16x32_bf16 v[38:41], v[142:145], v[198:201], v[38:41]
	v_mfma_f32_16x16x32_bf16 v[30:33], v[134:137], v[206:209], v[30:33]
	v_mfma_f32_16x16x32_bf16 v[22:25], v[142:145], v[206:209], v[22:25]
	v_mfma_f32_16x16x32_bf16 v[14:17], v[134:137], v[222:225], v[14:17]
	v_mfma_f32_16x16x32_bf16 v[6:9], v[142:145], v[222:225], v[6:9]
	v_mfma_f32_16x16x32_bf16 v[58:61], v[146:149], v[186:189], v[58:61]
	v_mfma_f32_16x16x32_bf16 v[50:53], v[154:157], v[186:189], v[50:53]
	v_mfma_f32_16x16x32_bf16 v[42:45], v[146:149], v[194:197], v[42:45]
	v_mfma_f32_16x16x32_bf16 v[34:37], v[154:157], v[194:197], v[34:37]
	v_mfma_f32_16x16x32_bf16 v[26:29], v[146:149], v[202:205], v[26:29]
	v_mfma_f32_16x16x32_bf16 v[18:21], v[154:157], v[202:205], v[18:21]
	v_mfma_f32_16x16x32_bf16 v[10:13], v[146:149], v[218:221], v[10:13]
	v_mfma_f32_16x16x32_bf16 v[2:5], v[154:157], v[218:221], v[2:5]
	v_mfma_f32_16x16x32_bf16 v[58:61], v[150:153], v[190:193], v[58:61]
	v_mfma_f32_16x16x32_bf16 v[50:53], v[182:185], v[190:193], v[50:53]
	v_mfma_f32_16x16x32_bf16 v[42:45], v[150:153], v[198:201], v[42:45]
	v_mfma_f32_16x16x32_bf16 v[34:37], v[182:185], v[198:201], v[34:37]
	v_mfma_f32_16x16x32_bf16 v[26:29], v[150:153], v[206:209], v[26:29]
	v_mfma_f32_16x16x32_bf16 v[18:21], v[182:185], v[206:209], v[18:21]
	v_mfma_f32_16x16x32_bf16 v[10:13], v[150:153], v[222:225], v[10:13]
	v_mfma_f32_16x16x32_bf16 v[2:5], v[182:185], v[222:225], v[2:5]
	s_setprio 0
	s_barrier
; #define PG8_STAGE(bufoff, gbase, voff) do { _Pragma("unroll") for (int _i = 0; _i < 2; ++_i) \
;         __builtin_amdgcn_global_load_lds((const unsigned*)((const char*)(gbase) + (voff)[_i]), (LAS unsigned*)(lds + (bufoff) + ldsw + _i * 8192), 16, 0, 0); } while (0)
; #define PG8_LDA(dst, b, h) do { _Pragma("unroll") for (int m = 0; m < 4; ++m) _Pragma("unroll") for (int k = 0; k < 2; ++k) dst[m][k] = *(const LAS bf16x8*)(lds + PG8_SA(b, h) + aoff + m * 2048 + k * 1024); } while (0)
; #define PG8_LDB(dst, b, h) do { _Pragma("unroll") for (int n = 0; n < 2; ++n) _Pragma("unroll") for (int k = 0; k < 2; ++k) dst[n][k] = *(const LAS bf16x8*)(lds + PG8_SB(b, h) + boff + n * 2048 + k * 1024); } while (0)
; #define PG8_WAIT_V(n) asm volatile("s_waitcnt vmcnt(" #n ")" ::: "memory")
; #define PG8_WAIT_L(n) asm volatile("s_waitcnt lgkmcnt(" #n ")" ::: "memory")
; __device__ __forceinline__ void gemm_phase(LAS unsigned char* lds, const Gemm g, const StaticOrder& S, const Epi& E) {
;     ...
;         for (int t = 0; t < nt; t += 2) {
;             const bool last = (t == nt - 2);
;             const char* a1 = cA + (size_t)(t + 1) * kstep;
;             const char* a2 = last ? nA : cA + (size_t)(t + 2) * kstep; const char* b2 = last ? nB : cB + (size_t)(t + 2) * kstep;
;             const char* a3 = a2 + kstep; const char* b3 = b2 + kstep;
;             PG8_LDB(B0, 0, 0); PG8_LDB(B1, 0, 1); PG8_SCHED; PG8_LDA(At, 0, 0); PG8_STAGE(PG8_SA(1, 1), a1 + hstepA, voffA);
;             PG8_WAIT_V(8); PG8_WAIT_L(0); PG8_BAR; PG8_MMA(0, 0, At, B0); PG8_MMA(0, 1, At, B1); PG8_BAR; PG8_SCHED;
;             PG8_LDA(At, 0, 1); PG8_STAGE(PG8_SB(0, 0), b2, voffB); PG8_STAGE(PG8_SB(0, 1), b2 + hstepB, voffB); PG8_STAGE(PG8_SA(0, 0), a2, voffA);
;             PG8_WAIT_V(8); PG8_WAIT_L(0); PG8_BAR; PG8_MMA(1, 0, At, B0); PG8_MMA(1, 1, At, B1); PG8_BAR; PG8_SCHED;
;             PG8_LDB(B0, 1, 0); PG8_LDB(B1, 1, 1); PG8_SCHED; PG8_LDA(At, 1, 0); PG8_STAGE(PG8_SA(0, 1), a2 + hstepA, voffA);
;             PG8_WAIT_V(8); PG8_WAIT_L(0); PG8_BAR; PG8_MMA(0, 0, At, B0); PG8_MMA(0, 1, At, B1); PG8_BAR; PG8_SCHED;
;             PG8_LDA(At, 1, 1); PG8_STAGE(PG8_SB(1, 0), b3, voffB); PG8_STAGE(PG8_SB(1, 1), b3 + hstepB, voffB); PG8_STAGE(PG8_SA(1, 0), a3, voffA);
;             PG8_WAIT_V(8); PG8_WAIT_L(0); PG8_BAR; PG8_MMA(1, 0, At, B0); PG8_MMA(1, 1, At, B1); PG8_BAR; PG8_SCHED;
	ds_read_b128 v[130:133], v228
	ds_read_b128 v[134:137], v228 offset:1024
	ds_read_b128 v[138:141], v228 offset:2048
	ds_read_b128 v[142:145], v228 offset:3072
	ds_read_b128 v[146:149], v229
	ds_read_b128 v[150:153], v229 offset:1024
	ds_read_b128 v[154:157], v229 offset:2048
	ds_read_b128 v[182:185], v229 offset:3072
	s_mov_b32 m0, s92
	ds_read_b128 v[186:189], v217 offset:32768
	ds_read_b128 v[190:193], v217 offset:33792
	ds_read_b128 v[194:197], v217 offset:34816
	ds_read_b128 v[198:201], v217 offset:35840
	ds_read_b128 v[202:205], v217 offset:36864
	ds_read_b128 v[206:209], v217 offset:37888
	ds_read_b128 v[218:221], v217 offset:38912
	ds_read_b128 v[222:225], v217 offset:39936
	global_load_lds_dwordx4 v178, s[2:3]
	s_mov_b32 m0, s93
	s_nop 0
	global_load_lds_dwordx4 v180, s[2:3]
	s_waitcnt vmcnt(8) lgkmcnt(0)
	s_barrier
	s_setprio 1
	v_mfma_f32_16x16x32_bf16 v[114:117], v[130:133], v[186:189], v[114:117]
	v_mfma_f32_16x16x32_bf16 v[126:129], v[138:141], v[186:189], v[126:129]
	v_mfma_f32_16x16x32_bf16 v[110:113], v[130:133], v[194:197], v[110:113]
	v_mfma_f32_16x16x32_bf16 v[102:105], v[138:141], v[194:197], v[102:105]
	v_mfma_f32_16x16x32_bf16 v[94:97], v[130:133], v[202:205], v[94:97]
	v_mfma_f32_16x16x32_bf16 v[86:89], v[138:141], v[202:205], v[86:89]
	v_mfma_f32_16x16x32_bf16 v[78:81], v[130:133], v[218:221], v[78:81]
	v_mfma_f32_16x16x32_bf16 v[70:73], v[138:141], v[218:221], v[70:73]
	v_mfma_f32_16x16x32_bf16 v[114:117], v[134:137], v[190:193], v[114:117]
	v_mfma_f32_16x16x32_bf16 v[126:129], v[142:145], v[190:193], v[126:129]
	v_mfma_f32_16x16x32_bf16 v[110:113], v[134:137], v[198:201], v[110:113]
	v_mfma_f32_16x16x32_bf16 v[102:105], v[142:145], v[198:201], v[102:105]
	v_mfma_f32_16x16x32_bf16 v[94:97], v[134:137], v[206:209], v[94:97]
	v_mfma_f32_16x16x32_bf16 v[86:89], v[142:145], v[206:209], v[86:89]
	v_mfma_f32_16x16x32_bf16 v[78:81], v[134:137], v[222:225], v[78:81]
	v_mfma_f32_16x16x32_bf16 v[70:73], v[142:145], v[222:225], v[70:73]
	v_mfma_f32_16x16x32_bf16 v[122:125], v[146:149], v[186:189], v[122:125]
	v_mfma_f32_16x16x32_bf16 v[118:121], v[154:157], v[186:189], v[118:121]
	v_mfma_f32_16x16x32_bf16 v[106:109], v[146:149], v[194:197], v[106:109]
	v_mfma_f32_16x16x32_bf16 v[98:101], v[154:157], v[194:197], v[98:101]
	v_mfma_f32_16x16x32_bf16 v[90:93], v[146:149], v[202:205], v[90:93]
	v_mfma_f32_16x16x32_bf16 v[82:85], v[154:157], v[202:205], v[82:85]
	v_mfma_f32_16x16x32_bf16 v[74:77], v[146:149], v[218:221], v[74:77]
	v_mfma_f32_16x16x32_bf16 v[66:69], v[154:157], v[218:221], v[66:69]
	v_mfma_f32_16x16x32_bf16 v[122:125], v[150:153], v[190:193], v[122:125]
	v_mfma_f32_16x16x32_bf16 v[118:121], v[182:185], v[190:193], v[118:121]
	v_mfma_f32_16x16x32_bf16 v[106:109], v[150:153], v[198:201], v[106:109]
	v_mfma_f32_16x16x32_bf16 v[98:101], v[182:185], v[198:201], v[98:101]
	v_mfma_f32_16x16x32_bf16 v[90:93], v[150:153], v[206:209], v[90:93]
	v_mfma_f32_16x16x32_bf16 v[82:85], v[182:185], v[206:209], v[82:85]
	v_mfma_f32_16x16x32_bf16 v[74:77], v[150:153], v[222:225], v[74:77]
	v_mfma_f32_16x16x32_bf16 v[66:69], v[182:185], v[222:225], v[66:69]
	s_setprio 0
	s_barrier
	s_add_u32 s40, s40, 0x80
	s_addc_u32 s41, s41, 0
	s_sub_u32 s100, s40, s52
	s_subb_u32 s101, s41, s53
	s_add_u32 s2, s2, 0x80
	s_addc_u32 s3, s3, 0
	s_add_i32 vcc_lo, s25, s70
	s_mov_b32 m0, vcc_lo
	ds_read_b128 v[186:189], v217 offset:49152
	ds_read_b128 v[190:193], v217 offset:50176
	ds_read_b128 v[194:197], v217 offset:51200
	ds_read_b128 v[198:201], v217 offset:52224
	ds_read_b128 v[202:205], v217 offset:53248
	ds_read_b128 v[206:209], v217 offset:54272
	ds_read_b128 v[218:221], v217 offset:55296
	ds_read_b128 v[222:225], v217 offset:56320
	global_load_lds_dwordx4 v160, s[100:101]
	s_add_i32 m0, vcc_lo, 0x2000
	s_add_i32 vcc_lo, s26, s70
	global_load_lds_dwordx4 v164, s[100:101]
	s_mov_b32 m0, vcc_lo
	s_nop 0
	global_load_lds_dwordx4 v160, s[40:41]
	s_add_i32 m0, vcc_lo, 0x2000
	s_nop 0
	global_load_lds_dwordx4 v164, s[40:41]
	s_mov_b32 m0, s58
	s_nop 0
	global_load_lds_dwordx4 v158, s[2:3]
	s_mov_b32 m0, s59
	s_nop 0
	global_load_lds_dwordx4 v162, s[2:3]
	s_waitcnt vmcnt(8) lgkmcnt(0)
	s_barrier
	s_setprio 1
	v_mfma_f32_16x16x32_bf16 v[62:65], v[130:133], v[186:189], v[62:65]
	v_mfma_f32_16x16x32_bf16 v[54:57], v[138:141], v[186:189], v[54:57]
	v_mfma_f32_16x16x32_bf16 v[46:49], v[130:133], v[194:197], v[46:49]
	v_mfma_f32_16x16x32_bf16 v[38:41], v[138:141], v[194:197], v[38:41]
	v_mfma_f32_16x16x32_bf16 v[30:33], v[130:133], v[202:205], v[30:33]
	v_mfma_f32_16x16x32_bf16 v[22:25], v[138:141], v[202:205], v[22:25]
	v_mfma_f32_16x16x32_bf16 v[14:17], v[130:133], v[218:221], v[14:17]
	v_mfma_f32_16x16x32_bf16 v[6:9], v[138:141], v[218:221], v[6:9]
	v_mfma_f32_16x16x32_bf16 v[62:65], v[134:137], v[190:193], v[62:65]
	v_mfma_f32_16x16x32_bf16 v[54:57], v[142:145], v[190:193], v[54:57]
	v_mfma_f32_16x16x32_bf16 v[46:49], v[134:137], v[198:201], v[46:49]
	v_mfma_f32_16x16x32_bf16 v[38:41], v[142:145], v[198:201], v[38:41]
	v_mfma_f32_16x16x32_bf16 v[30:33], v[134:137], v[206:209], v[30:33]
	v_mfma_f32_16x16x32_bf16 v[22:25], v[142:145], v[206:209], v[22:25]
	v_mfma_f32_16x16x32_bf16 v[14:17], v[134:137], v[222:225], v[14:17]
	v_mfma_f32_16x16x32_bf16 v[6:9], v[142:145], v[222:225], v[6:9]
	v_mfma_f32_16x16x32_bf16 v[58:61], v[146:149], v[186:189], v[58:61]
	v_mfma_f32_16x16x32_bf16 v[50:53], v[154:157], v[186:189], v[50:53]
	v_mfma_f32_16x16x32_bf16 v[42:45], v[146:149], v[194:197], v[42:45]
	v_mfma_f32_16x16x32_bf16 v[34:37], v[154:157], v[194:197], v[34:37]
	v_mfma_f32_16x16x32_bf16 v[26:29], v[146:149], v[202:205], v[26:29]
	v_mfma_f32_16x16x32_bf16 v[18:21], v[154:157], v[202:205], v[18:21]
	v_mfma_f32_16x16x32_bf16 v[10:13], v[146:149], v[218:221], v[10:13]
	v_mfma_f32_16x16x32_bf16 v[2:5], v[154:157], v[218:221], v[2:5]
	v_mfma_f32_16x16x32_bf16 v[58:61], v[150:153], v[190:193], v[58:61]
	v_mfma_f32_16x16x32_bf16 v[50:53], v[182:185], v[190:193], v[50:53]
	v_mfma_f32_16x16x32_bf16 v[42:45], v[150:153], v[198:201], v[42:45]
	v_mfma_f32_16x16x32_bf16 v[34:37], v[182:185], v[198:201], v[34:37]
	v_mfma_f32_16x16x32_bf16 v[26:29], v[150:153], v[206:209], v[26:29]
	v_mfma_f32_16x16x32_bf16 v[18:21], v[182:185], v[206:209], v[18:21]
	v_mfma_f32_16x16x32_bf16 v[10:13], v[150:153], v[222:225], v[10:13]
	v_mfma_f32_16x16x32_bf16 v[2:5], v[182:185], v[222:225], v[2:5]
	s_setprio 0
	s_barrier
	s_add_u32 s0, s0, 0x100
	s_addc_u32 s1, s1, 0
	s_add_u32 s5, s5, 0x100
	s_addc_u32 s16, s16, 0
	s_cmp_ge_i32 s27, s84
	s_mov_b32 s17, s27
	s_cbranch_scc0 .LBB0_177
	s_and_b64 vcc, exec, s[74:75]
	s_cbranch_vccz .LBB0_180
